# GEMM idle-tail weight-copy pulls 2 (G1) / 1 (G3) items per idle workgroup; on top of PW walk prefetch
# speedup vs baseline: 1.0019x; 1.0019x over previous
.LBB0_406:
	v_readlane_b32 s0, v255, 2
	s_cmp_eq_u32 s0, 3
	v_readlane_b32 s1, v255, 3
	s_cbranch_scc1 .LBB0_469
	v_readlane_b32 s0, v253, 48
	v_readlane_b32 s1, v253, 49
	s_andn2_b64 vcc, exec, s[0:1]
	s_cbranch_vccnz .LBB0_469
	v_readlane_b32 s0, v255, 2
	v_readlane_b32 s8, v250, 5
	v_readlane_b32 s1, v255, 3
	v_mov_b32_e32 v2, v0
	v_readlane_b32 s9, v250, 6
	v_readlane_b32 s10, v250, 7
	v_readlane_b32 s11, v250, 8
	v_readlane_b32 s14, v250, 11
	v_readlane_b32 s15, v250, 12
	v_readlane_b32 s16, v250, 13
	v_readlane_b32 s17, v250, 14
	v_readlane_b32 s18, v250, 15
	v_readlane_b32 s19, v250, 16
	s_add_i32 s0, s0, 1
	s_cmp_eq_u32 s0, 1
	s_cselect_b32 s0, 0, s0
	v_readlane_b32 s12, v250, 9
	v_readfirstlane_b32 s1, v2
	v_readlane_b32 s13, v250, 10
	s_mov_b64 s[10:11], s[14:15]
	s_mov_b64 s[4:5], s[18:19]
	s_mov_b64 s[2:3], s[62:63]
	s_mov_b64 s[8:9], s[16:17]
	v_cmp_eq_u32_e32 vcc, 0, v2
	v_readlane_b32 s20, v250, 17
	v_readlane_b32 s21, v250, 18
	v_readlane_b32 s22, v250, 19
	v_readlane_b32 s23, v250, 20
	s_waitcnt vmcnt(0)
	s_barrier
	s_and_saveexec_b64 s[12:13], vcc
	s_cbranch_execz .LBB0_412
	s_mov_b64 s[16:17], exec
	v_mbcnt_lo_u32_b32 v3, s16, 0
	v_mbcnt_hi_u32_b32 v3, s17, v3
	v_cmp_eq_u32_e32 vcc, 0, v3
	s_and_saveexec_b64 s[14:15], vcc
	s_cbranch_execz .LBB0_411
	s_lshl_b32 s28, s0, 6
	s_lshl_b64 s[18:19], s[28:29], 2
	v_readlane_b32 s20, v252, 11
	s_add_u32 s18, s20, s18
	v_readlane_b32 s20, v252, 12
	s_addc_u32 s19, s20, s19
	v_readlane_b32 s20, v255, 2
	s_cmp_eq_u32 s20, 0
	s_cselect_b32 s20, 0x80, 0
	s_add_u32 s18, s18, s20
	s_addc_u32 s19, s19, 0
	s_bcnt1_i32_b64 s16, s[16:17]
	v_readlane_b32 s20, v255, 2
	s_cmp_eq_u32 s20, 0
	s_cselect_b32 s20, 13, 2
	s_mul_i32 s16, s16, s20
	s_waitcnt lgkmcnt(1)
	v_mov_b32_e32 v4, s16
	global_atomic_add v4, v67, v4, s[18:19] sc0
.LBB0_411:
	s_or_b64 exec, exec, s[14:15]
	s_waitcnt vmcnt(0) lgkmcnt(1)
	v_readfirstlane_b32 s14, v4
	s_nop 1
	v_mad_u32_u24 v3, v3, 2, s14
	v_readlane_b32 s14, v254, 19
	s_nop 1
	v_mov_b32_e32 v4, s14
	ds_write_b32 v4, v3
.LBB0_412:
	s_or_b64 exec, exec, s[12:13]
	v_readlane_b32 s12, v254, 19
	s_waitcnt lgkmcnt(0)
	s_barrier
	v_mov_b32_e32 v3, s12
	ds_read_b32 v3, v3
	s_waitcnt lgkmcnt(0)
	v_readfirstlane_b32 s25, v3
	v_readlane_b32 s12, v255, 2
	s_cmp_eq_u32 s12, 0
	s_cselect_b32 s12, 0x600, 0
	s_add_i32 s25, s25, s12
	s_cmpk_gt_i32 s25, 0xc3f
	s_cbranch_scc1 .LBB0_468
	s_ashr_i32 s14, s1, 6
	s_mul_i32 s16, s0, 0x2c00000
	s_mul_hi_u32 s17, s0, 0x2c00000
	s_add_u32 s4, s4, s16
	s_addc_u32 s5, s5, s17
	s_mul_i32 s13, s0, 0x5800000
	s_mov_b32 s1, s29
	s_mul_hi_u32 s12, s0, 0x5800000
	s_add_u32 s8, s8, s13
	s_addc_u32 s9, s9, s12
	s_lshl_b64 s[12:13], s[0:1], 24
	s_add_u32 s10, s10, s12
	s_addc_u32 s11, s11, s13
	s_mul_i32 s12, s0, 0x3000000
	v_bfe_u32 v3, v2, 5, 1
	s_mul_hi_u32 s13, s0, 0x3000000
	s_add_u32 s12, s2, s12
	s_addc_u32 s13, s3, s13
	v_lshlrev_b32_e32 v5, 1, v3
	s_lshl_b32 s2, s14, 3
	v_lshlrev_b32_e32 v3, 2, v3
	v_and_b32_e32 v4, 31, v2
	v_or_b32_e32 v6, s2, v3
	v_bfe_u32 v7, v2, 4, 2
	v_lshlrev_b32_e32 v8, 4, v2
	v_lshlrev_b32_e32 v2, 3, v2
	v_lshl_or_b32 v52, s14, 2, v5
	v_lshlrev_b32_e32 v53, 2, v4
	v_lshlrev_b32_e32 v54, 10, v4
	v_lshlrev_b32_e32 v5, 3, v4
	v_and_b32_e32 v4, 0x78, v2
	v_add_u32_e32 v2, 64, v6
	s_lshl_b32 s3, s14, 4
	v_bitop3_b32 v56, s2, v5, v3 bitop3:0x36
	v_xor_b32_e32 v57, v2, v5
	v_add_u32_e32 v2, 0x80, v6
	s_lshl_b32 s2, s14, 5
	v_mov_b32_e32 v3, 0xf0
	v_xor_b32_e32 v58, v2, v5
	v_add_u32_e32 v2, 0xc0, v6
	v_bitop3_b32 v61, s2, v3, v8 bitop3:0x48
	s_or_b32 s2, s3, 8
	v_xor_b32_e32 v59, v2, v5
	v_or_b32_e32 v2, s2, v7
	s_lshl_b32 s2, s2, 1
	s_sub_i32 s18, 0xc40, s25
	v_bitop3_b32 v63, s2, v3, v8 bitop3:0x48
	s_or_b32 s2, s3, 12
	v_readlane_b32 s51, v255, 2
	s_cmp_eq_u32 s51, 0
	s_cselect_b32 s51, 13, 2
	s_min_i32 s51, s18, s51
	v_lshlrev_b32_e32 v62, 8, v2
	v_or_b32_e32 v2, s2, v7
	s_lshl_b32 s2, s2, 1
	s_mul_i32 s14, s0, 0x1600000
	s_max_i32 s22, s51, 1
	v_readlane_b32 s18, v252, 13
	s_mul_hi_u32 s15, s0, 0x1600000
	s_add_u32 s14, s18, s14
	v_readlane_b32 s18, v252, 14
	s_addc_u32 s15, s18, s15
	v_readlane_b32 s18, v252, 15
	s_add_u32 s16, s18, s16
	v_readlane_b32 s18, v252, 16
	v_or_b32_e32 v55, s3, v7
	v_bitop3_b32 v65, s2, v3, v8 bitop3:0x48
	s_mul_hi_u32 s2, s0, 0x1b00000
	s_mul_i32 s3, s0, 0x1b00000
	s_addc_u32 s17, s18, s17
	s_lshl_b64 s[0:1], s[0:1], 23
	v_readlane_b32 s18, v252, 17
	s_add_u32 s18, s18, s0
	v_readlane_b32 s0, v252, 18
	s_addc_u32 s19, s0, s1
	v_readlane_b32 s0, v252, 1
	v_lshlrev_b32_e32 v64, 8, v2
	s_add_u32 s20, s0, s3
	v_readlane_b32 s0, v252, 2
	v_mov_b32_e32 v2, 0
	s_mov_b32 s50, 1
	v_lshlrev_b32_e32 v60, 8, v55
	s_addc_u32 s21, s0, s2
	s_lshl_b32 s52, s22, 3
	s_lshl_b32 s53, s25, 7
	s_lshl_b32 s54, s25, 3
	s_mov_b64 s[22:23], 0
	s_mov_b32 s55, 0
	v_lshlrev_b32_e32 v66, 1, v4
	s_mov_b32 s56, 0
	v_mov_b32_e32 v3, v2
	v_mov_b32_e32 v4, v2
	v_mov_b32_e32 v5, v2
	v_mov_b32_e32 v10, v2
	v_mov_b32_e32 v11, v2
	v_mov_b32_e32 v12, v2
	v_mov_b32_e32 v13, v2
	v_mov_b32_e32 v18, v2
	v_mov_b32_e32 v19, v2
	v_mov_b32_e32 v20, v2
	v_mov_b32_e32 v21, v2
	v_mov_b32_e32 v26, v2
	v_mov_b32_e32 v27, v2
	v_mov_b32_e32 v28, v2
	v_mov_b32_e32 v29, v2
	v_mov_b32_e32 v6, v2
	v_mov_b32_e32 v7, v2
	v_mov_b32_e32 v8, v2
	v_mov_b32_e32 v9, v2
	v_mov_b32_e32 v14, v2
	v_mov_b32_e32 v15, v2
	v_mov_b32_e32 v16, v2
	v_mov_b32_e32 v17, v2
	v_mov_b32_e32 v22, v2
	v_mov_b32_e32 v23, v2
	v_mov_b32_e32 v24, v2
	v_mov_b32_e32 v25, v2
	v_mov_b32_e32 v30, v2
	v_mov_b32_e32 v31, v2
	v_mov_b32_e32 v32, v2
	v_mov_b32_e32 v33, v2
	s_branch .LBB0_415

.LBB0_1630:
	v_readlane_b32 s0, v255, 2
	s_cmp_eq_u32 s0, 3
	v_readlane_b32 s1, v255, 3
	s_cbranch_scc1 .LBB0_1693
	v_readlane_b32 s0, v253, 59
	v_readlane_b32 s1, v253, 60
	s_andn2_b64 vcc, exec, s[0:1]
	s_cbranch_vccnz .LBB0_1693
	v_readlane_b32 s0, v255, 2
	v_readlane_b32 s4, v250, 5
	v_readlane_b32 s1, v255, 3
	v_mov_b32_e32 v2, v0
	v_readlane_b32 s5, v250, 6
	v_readlane_b32 s6, v250, 7
	v_readlane_b32 s7, v250, 8
	v_readlane_b32 s8, v250, 9
	v_readlane_b32 s9, v250, 10
	v_readlane_b32 s10, v250, 11
	v_readlane_b32 s11, v250, 12
	v_readlane_b32 s12, v250, 13
	v_readlane_b32 s13, v250, 14
	v_readlane_b32 s14, v250, 15
	v_readlane_b32 s15, v250, 16
	s_add_i32 s0, s0, 1
	s_mov_b64 s[8:9], s[10:11]
	v_readfirstlane_b32 s1, v2
	s_mov_b64 s[4:5], s[14:15]
	s_mov_b64 s[2:3], s[62:63]
	s_mov_b64 s[6:7], s[12:13]
	v_cmp_eq_u32_e32 vcc, 0, v2
	v_readlane_b32 s16, v250, 17
	v_readlane_b32 s17, v250, 18
	v_readlane_b32 s18, v250, 19
	v_readlane_b32 s19, v250, 20
	s_waitcnt vmcnt(0)
	s_barrier
	s_and_saveexec_b64 s[10:11], vcc
	s_cbranch_execz .LBB0_1636
	s_mov_b64 s[14:15], exec
	v_mbcnt_lo_u32_b32 v3, s14, 0
	v_mbcnt_hi_u32_b32 v3, s15, v3
	v_cmp_eq_u32_e32 vcc, 0, v3
	s_and_saveexec_b64 s[12:13], vcc
	s_cbranch_execz .LBB0_1635
	s_lshl_b32 s28, s0, 6
	s_lshl_b64 s[16:17], s[28:29], 2
	v_readlane_b32 s18, v252, 11
	s_add_u32 s16, s18, s16
	v_readlane_b32 s18, v252, 12
	s_addc_u32 s17, s18, s17
	s_bcnt1_i32_b64 s14, s[14:15]
	s_mul_i32 s14, s14, 1
	v_mov_b32_e32 v4, s14
	global_atomic_add v4, v67, v4, s[16:17] sc0
.LBB0_1635:
	s_or_b64 exec, exec, s[12:13]
	s_waitcnt vmcnt(0)
	v_readfirstlane_b32 s12, v4
	s_nop 1
	v_mad_u32_u24 v3, v3, 1, s12
	v_readlane_b32 s12, v254, 19
	s_nop 1
	v_mov_b32_e32 v4, s12
	ds_write_b32 v4, v3
.LBB0_1636:
	s_or_b64 exec, exec, s[10:11]
	v_readlane_b32 s10, v254, 19
	s_waitcnt lgkmcnt(0)
	s_barrier
	v_mov_b32_e32 v3, s10
	ds_read_b32 v3, v3
	s_waitcnt lgkmcnt(0)
	v_readfirstlane_b32 s25, v3
	s_cmpk_gt_i32 s25, 0xc3f
	s_cbranch_scc1 .LBB0_1692
	s_ashr_i32 s12, s1, 6
	s_mul_i32 s14, s0, 0x2c00000
	s_mul_hi_u32 s15, s0, 0x2c00000
	s_add_u32 s4, s4, s14
	s_addc_u32 s5, s5, s15
	s_mul_i32 s11, s0, 0x5800000
	s_mov_b32 s1, s29
	s_mul_hi_u32 s10, s0, 0x5800000
	s_add_u32 s6, s6, s11
	s_addc_u32 s7, s7, s10
	s_lshl_b64 s[10:11], s[0:1], 24
	s_add_u32 s8, s8, s10
	s_addc_u32 s9, s9, s11
	s_mul_i32 s10, s0, 0x3000000
	v_bfe_u32 v3, v2, 5, 1
	s_mul_hi_u32 s11, s0, 0x3000000
	s_add_u32 s10, s2, s10
	s_addc_u32 s11, s3, s11
	v_lshlrev_b32_e32 v5, 1, v3
	s_lshl_b32 s2, s12, 3
	v_lshlrev_b32_e32 v3, 2, v3
	v_and_b32_e32 v4, 31, v2
	v_or_b32_e32 v6, s2, v3
	v_bfe_u32 v7, v2, 4, 2
	v_lshlrev_b32_e32 v8, 4, v2
	v_lshlrev_b32_e32 v2, 3, v2
	v_lshl_or_b32 v52, s12, 2, v5
	v_lshlrev_b32_e32 v53, 2, v4
	v_lshlrev_b32_e32 v54, 10, v4
	v_lshlrev_b32_e32 v5, 3, v4
	v_and_b32_e32 v4, 0x78, v2
	v_add_u32_e32 v2, 64, v6
	s_lshl_b32 s3, s12, 4
	v_bitop3_b32 v56, s2, v5, v3 bitop3:0x36
	v_xor_b32_e32 v57, v2, v5
	v_add_u32_e32 v2, 0x80, v6
	s_lshl_b32 s2, s12, 5
	v_mov_b32_e32 v3, 0xf0
	v_xor_b32_e32 v58, v2, v5
	v_add_u32_e32 v2, 0xc0, v6
	v_bitop3_b32 v61, s2, v3, v8 bitop3:0x48
	s_or_b32 s2, s3, 8
	v_xor_b32_e32 v59, v2, v5
	v_or_b32_e32 v2, s2, v7
	s_lshl_b32 s2, s2, 1
	s_sub_i32 s16, 0xc40, s25
	v_bitop3_b32 v63, s2, v3, v8 bitop3:0x48
	s_or_b32 s2, s3, 12
	s_min_i32 s51, s16, 1
	v_lshlrev_b32_e32 v62, 8, v2
	v_or_b32_e32 v2, s2, v7
	s_lshl_b32 s2, s2, 1
	s_mul_i32 s12, s0, 0x1600000
	s_max_i32 s20, s51, 1
	v_readlane_b32 s16, v252, 13
	s_mul_hi_u32 s13, s0, 0x1600000
	s_add_u32 s12, s16, s12
	v_readlane_b32 s16, v252, 14
	s_addc_u32 s13, s16, s13
	v_readlane_b32 s16, v252, 15
	s_add_u32 s14, s16, s14
	v_readlane_b32 s16, v252, 16
	v_or_b32_e32 v55, s3, v7
	v_bitop3_b32 v65, s2, v3, v8 bitop3:0x48
	s_mul_hi_u32 s2, s0, 0x1b00000
	s_mul_i32 s3, s0, 0x1b00000
	s_addc_u32 s15, s16, s15
	s_lshl_b64 s[0:1], s[0:1], 23
	v_readlane_b32 s16, v252, 17
	s_add_u32 s16, s16, s0
	v_readlane_b32 s0, v252, 18
	s_addc_u32 s17, s0, s1
	v_readlane_b32 s0, v252, 1
	v_lshlrev_b32_e32 v64, 8, v2
	s_add_u32 s18, s0, s3
	v_readlane_b32 s0, v252, 2
	v_mov_b32_e32 v2, 0
	s_mov_b32 s50, 1
	v_lshlrev_b32_e32 v60, 8, v55
	s_addc_u32 s19, s0, s2
	s_lshl_b32 s52, s20, 3
	s_lshl_b32 s53, s25, 7
	s_lshl_b32 s54, s25, 3
	s_mov_b64 s[22:23], 0
	s_mov_b32 s55, 0
	v_lshlrev_b32_e32 v66, 1, v4
	s_mov_b32 s56, 0
	v_mov_b32_e32 v3, v2
	v_mov_b32_e32 v4, v2
	v_mov_b32_e32 v5, v2
	v_mov_b32_e32 v10, v2
	v_mov_b32_e32 v11, v2
	v_mov_b32_e32 v12, v2
	v_mov_b32_e32 v13, v2
	v_mov_b32_e32 v18, v2
	v_mov_b32_e32 v19, v2
	v_mov_b32_e32 v20, v2
	v_mov_b32_e32 v21, v2
	v_mov_b32_e32 v26, v2
	v_mov_b32_e32 v27, v2
	v_mov_b32_e32 v28, v2
	v_mov_b32_e32 v29, v2
	v_mov_b32_e32 v6, v2
	v_mov_b32_e32 v7, v2
	v_mov_b32_e32 v8, v2
	v_mov_b32_e32 v9, v2
	v_mov_b32_e32 v14, v2
	v_mov_b32_e32 v15, v2
	v_mov_b32_e32 v16, v2
	v_mov_b32_e32 v17, v2
	v_mov_b32_e32 v22, v2
	v_mov_b32_e32 v23, v2
	v_mov_b32_e32 v24, v2
	v_mov_b32_e32 v25, v2
	v_mov_b32_e32 v30, v2
	v_mov_b32_e32 v31, v2
	v_mov_b32_e32 v32, v2
	v_mov_b32_e32 v33, v2
	s_branch .LBB0_1639
